# v5 + nt hint on the one-shot x row loads in phase 0 (keep XN and transposed weights in the infinity cache) run 1
# speedup vs baseline: 1.0286x; 1.0128x over previous
; __device__ __forceinline__ void rms_row2_2048(const float* xa, const float* xb, const float* g, bf16_t* oa, bf16_t* ob, int lane) {
;     const f32x4* ra = (const f32x4*)xa + lane; const f32x4* rb = (const f32x4*)xb + lane; const f32x4* gr = (const f32x4*)g + lane;
;     f32x4 va[8], vb[8]; float sa = 0.f, sb = 0.f;
; #pragma unroll
;     for (int j = 0; j < 8; ++j) { va[j] = ra[64 * j]; vb[j] = rb[64 * j]; }
; #pragma unroll
;     for (int j = 0; j < 8; ++j) { sa += (va[j].x * va[j].x + va[j].y * va[j].y) + (va[j].z * va[j].z + va[j].w * va[j].w); sb += (vb[j].x * vb[j].x + vb[j].y * vb[j].y) + (vb[j].z * vb[j].z + vb[j].w * vb[j].w); }
;     const float rsa = __builtin_amdgcn_rsqf(wave_sum(sa) * (1.f / DM) + EPS), rsb = __builtin_amdgcn_rsqf(wave_sum(sb) * (1.f / DM) + EPS);
; __device__ __forceinline__ void phase0(const Params& p, Frame& F) {
;     ...
;     for (int m = gw; m < T; m += 2 * NGW) { const int m2 = (m + NGW < T) ? m + NGW : m;
;         rms_row2_2048(p.in[I_X] + (size_t)m * DM, p.in[I_X] + (size_t)m2 * DM, p.in[I_GMIX], (bf16_t*)(ws + WS_XN) + (size_t)m * DM, (bf16_t*)(ws + WS_XN) + (size_t)m2 * DM, lane); }
.LBB0_75:
	s_add_i32 s3, s0, s16
	s_cmp_lt_i32 s3, 0x8000
	s_cselect_b32 s4, s3, s0
	s_ashr_i32 s1, s0, 31
	s_lshl_b64 s[6:7], s[0:1], 13
	v_lshl_add_u64 v[0:1], v[46:47], 0, s[6:7]
	global_load_dwordx4 v[72:75], v[0:1], off nt
	global_load_dwordx4 v[68:71], v[48:49], off
	s_ashr_i32 s5, s4, 31
	global_load_dwordx4 v[76:79], v[0:1], off offset:1024 nt
	global_load_dwordx4 v[80:83], v[0:1], off offset:2048 nt
	global_load_dwordx4 v[36:39], v[0:1], off offset:3072 nt
	s_lshl_b64 s[6:7], s[4:5], 13
	v_add_co_u32_e32 v6, vcc, s2, v0
	v_lshl_add_u64 v[4:5], v[46:47], 0, s[6:7]
	s_nop 0
	v_addc_co_u32_e32 v7, vcc, 0, v1, vcc
	v_add_co_u32_e32 v96, vcc, s2, v4
	global_load_dwordx4 v[84:87], v[4:5], off nt
	global_load_dwordx4 v[88:91], v[4:5], off offset:1024 nt
	global_load_dwordx4 v[92:95], v[4:5], off offset:2048 nt
	global_load_dwordx4 v[32:35], v[4:5], off offset:3072 nt
	global_load_dwordx4 v[28:31], v[6:7], off nt
	global_load_dwordx4 v[20:23], v[6:7], off offset:1024 nt
	global_load_dwordx4 v[12:15], v[6:7], off offset:2048 nt
	global_load_dwordx4 v[0:3], v[6:7], off offset:3072 nt
	v_addc_co_u32_e32 v97, vcc, 0, v5, vcc
	global_load_dwordx4 v[24:27], v[96:97], off nt
	global_load_dwordx4 v[16:19], v[96:97], off offset:1024 nt
	global_load_dwordx4 v[8:11], v[96:97], off offset:2048 nt
	global_load_dwordx4 v[4:7], v[96:97], off offset:3072 nt
	s_lshl_b64 s[0:1], s[0:1], 12
	v_lshl_add_u64 v[58:59], v[44:45], 0, s[0:1]
	s_lshl_b64 s[0:1], s[4:5], 12
	v_lshl_add_u64 v[60:61], v[44:45], 0, s[0:1]
	s_add_i32 s0, s3, s16
	s_cmpk_gt_i32 s0, 0x7fff
	s_waitcnt vmcnt(16)
	v_mul_f32_e32 v43, v73, v73
	v_mul_f32_e32 v96, v75, v75
	s_waitcnt vmcnt(14)
	v_mul_f32_e32 v97, v77, v77
	v_mul_f32_e32 v98, v79, v79
	v_fmac_f32_e32 v43, v72, v72
	v_fmac_f32_e32 v96, v74, v74
	s_waitcnt vmcnt(11)
	v_mul_f32_e32 v103, v85, v85
	v_mul_f32_e32 v104, v87, v87
	v_fmac_f32_e32 v97, v76, v76
	v_fmac_f32_e32 v98, v78, v78
	s_waitcnt vmcnt(10)
	v_mul_f32_e32 v105, v89, v89
	v_mul_f32_e32 v106, v91, v91
	v_mul_f32_e32 v99, v81, v81
	v_mul_f32_e32 v100, v83, v83
	s_waitcnt vmcnt(9)
	v_mul_f32_e32 v107, v93, v93
	v_mul_f32_e32 v108, v95, v95
	v_add_f32_e32 v43, v43, v96
	v_fmac_f32_e32 v103, v84, v84
	v_fmac_f32_e32 v104, v86, v86
	v_add_f32_e32 v96, v97, v98
	v_fmac_f32_e32 v105, v88, v88
	v_fmac_f32_e32 v106, v90, v90
	v_mul_f32_e32 v101, v37, v37
	v_mul_f32_e32 v102, v39, v39
	v_fmac_f32_e32 v99, v80, v80
	v_fmac_f32_e32 v100, v82, v82
	s_waitcnt vmcnt(8)
	v_mul_f32_e32 v109, v33, v33
	v_mul_f32_e32 v110, v35, v35
	v_fmac_f32_e32 v107, v92, v92
	v_fmac_f32_e32 v108, v94, v94
	v_add_f32_e32 v103, v103, v104
	v_add_f32_e32 v43, v43, v96
	v_add_f32_e32 v96, v105, v106
	v_fmac_f32_e32 v101, v36, v36
	v_fmac_f32_e32 v102, v38, v38
	s_waitcnt vmcnt(7)
	v_mul_f32_e32 v111, v29, v29
	v_mul_f32_e32 v112, v31, v31
	v_add_f32_e32 v97, v99, v100
	v_fmac_f32_e32 v109, v32, v32
	v_fmac_f32_e32 v110, v34, v34
	s_waitcnt vmcnt(3)
	v_mul_f32_e32 v99, v25, v25
	v_mul_f32_e32 v100, v27, v27
	v_add_f32_e32 v104, v107, v108
	v_add_f32_e32 v96, v103, v96
	v_mul_f32_e32 v113, v21, v21
	v_mul_f32_e32 v114, v23, v23
	v_add_f32_e32 v98, v101, v102
	v_fmac_f32_e32 v111, v28, v28
	v_fmac_f32_e32 v112, v30, v30
	s_waitcnt vmcnt(2)
	v_mul_f32_e32 v101, v17, v17
	v_mul_f32_e32 v102, v19, v19
	v_add_f32_e32 v105, v109, v110
	v_fmac_f32_e32 v99, v24, v24
	v_fmac_f32_e32 v100, v26, v26
	v_add_f32_e32 v43, v43, v97
	v_add_f32_e32 v96, v96, v104
	v_mul_f32_e32 v115, v13, v13
	v_mul_f32_e32 v116, v15, v15
	v_fmac_f32_e32 v113, v20, v20
	v_fmac_f32_e32 v114, v22, v22
	s_waitcnt vmcnt(1)
	v_mul_f32_e32 v119, v9, v9
	v_mul_f32_e32 v120, v11, v11
	v_add_f32_e32 v106, v111, v112
	v_fmac_f32_e32 v101, v16, v16
	v_fmac_f32_e32 v102, v18, v18
	v_add_f32_e32 v97, v99, v100
	v_add_f32_e32 v43, v43, v98
	v_add_f32_e32 v96, v96, v105
	v_mul_f32_e32 v117, v1, v1
	v_mul_f32_e32 v118, v3, v3
	v_fmac_f32_e32 v115, v12, v12
	v_fmac_f32_e32 v116, v14, v14
	s_waitcnt vmcnt(0)
	v_mul_f32_e32 v121, v5, v5
	v_mul_f32_e32 v122, v7, v7
	v_add_f32_e32 v107, v113, v114
	v_fmac_f32_e32 v119, v8, v8
	v_fmac_f32_e32 v120, v10, v10
	v_add_f32_e32 v99, v101, v102
	v_add_f32_e32 v43, v43, v106
	v_add_f32_e32 v96, v96, v97
	v_fmac_f32_e32 v117, v0, v0
	v_fmac_f32_e32 v118, v2, v2
	v_add_f32_e32 v108, v115, v116
	v_fmac_f32_e32 v121, v4, v4
	v_fmac_f32_e32 v122, v6, v6
	v_add_f32_e32 v100, v119, v120
	v_add_f32_e32 v43, v43, v107
	v_add_f32_e32 v96, v96, v99
	v_add_f32_e32 v109, v117, v118
	v_add_f32_e32 v101, v121, v122
	v_add_f32_e32 v43, v43, v108
	v_add_f32_e32 v96, v96, v100
	v_add_f32_e32 v43, v43, v109
	v_add_f32_e32 v96, v96, v101
	ds_bpermute_b32 v97, v62, v43
	ds_bpermute_b32 v98, v62, v96
	s_waitcnt lgkmcnt(1)
	v_add_f32_e32 v43, v43, v97
	s_waitcnt lgkmcnt(0)
	v_add_f32_e32 v96, v96, v98
	ds_bpermute_b32 v97, v63, v43
	ds_bpermute_b32 v98, v63, v96
	s_waitcnt lgkmcnt(1)
	v_add_f32_e32 v43, v43, v97
	s_waitcnt lgkmcnt(0)
	v_add_f32_e32 v96, v96, v98
	ds_bpermute_b32 v97, v64, v43
	ds_bpermute_b32 v98, v64, v96
	s_waitcnt lgkmcnt(1)
	v_add_f32_e32 v43, v43, v97
	s_waitcnt lgkmcnt(0)
	v_add_f32_e32 v96, v96, v98
	ds_bpermute_b32 v97, v65, v43
	ds_bpermute_b32 v98, v65, v96
	s_waitcnt lgkmcnt(1)
	v_add_f32_e32 v43, v43, v97
	s_waitcnt lgkmcnt(0)
	v_add_f32_e32 v96, v96, v98
	ds_bpermute_b32 v97, v66, v43
	ds_bpermute_b32 v98, v66, v96
	s_waitcnt lgkmcnt(1)
	v_add_f32_e32 v43, v43, v97
	s_waitcnt lgkmcnt(0)
	v_add_f32_e32 v96, v96, v98
	ds_bpermute_b32 v97, v67, v43
	ds_bpermute_b32 v98, v67, v96
	s_waitcnt lgkmcnt(1)
	v_add_f32_e32 v43, v43, v97
	s_waitcnt lgkmcnt(0)
; __device__ __forceinline__ unsigned pk2(float lo, float hi) { return cvt_pk_bf16(lo, hi); }
; __device__ __forceinline__ void rms_row2_2048(const float* xa, const float* xb, const float* g, bf16_t* oa, bf16_t* ob, int lane) {
;     ...
;     const float rsa = __builtin_amdgcn_rsqf(wave_sum(sa) * (1.f / DM) + EPS), rsb = __builtin_amdgcn_rsqf(wave_sum(sb) * (1.f / DM) + EPS);
;     u32x2* o8a = (u32x2*)oa + lane; u32x2* o8b = (u32x2*)ob + lane;
; #pragma unroll
;     for (int j = 0; j < 8; ++j) { const f32x4 gg = gr[64 * j]; u32x2 w;
;         w.x = pk2(va[j].x * rsa * gg.x, va[j].y * rsa * gg.y); w.y = pk2(va[j].z * rsa * gg.z, va[j].w * rsa * gg.w); o8a[64 * j] = w;
;         w.x = pk2(vb[j].x * rsb * gg.x, vb[j].y * rsb * gg.y); w.y = pk2(vb[j].z * rsb * gg.z, vb[j].w * rsb * gg.w); o8b[64 * j] = w; }
; __device__ __forceinline__ void phase0(const Params& p, Frame& F) {
;     ...
;     for (int m = gw; m < T; m += 2 * NGW) { const int m2 = (m + NGW < T) ? m + NGW : m;
;         rms_row2_2048(p.in[I_X] + (size_t)m * DM, p.in[I_X] + (size_t)m2 * DM, p.in[I_GMIX], (bf16_t*)(ws + WS_XN) + (size_t)m * DM, (bf16_t*)(ws + WS_XN) + (size_t)m2 * DM, lane); }
	v_add_f32_e32 v96, v96, v98
	v_fmamk_f32 v43, v43, 0x3a000000, v41
	v_fmamk_f32 v96, v96, 0x3a000000, v41
	v_rsq_f32_e32 v43, v43
	v_rsq_f32_e32 v96, v96
	v_mul_f32_e32 v72, v72, v43
	v_mul_f32_e32 v73, v73, v43
	v_mul_f32_e32 v84, v84, v96
	v_mul_f32_e32 v85, v85, v96
	v_mul_f32_e32 v74, v74, v43
	v_mul_f32_e32 v75, v75, v43
	v_mul_f32_e32 v72, v72, v68
	v_mul_f32_e32 v73, v73, v69
	v_mul_f32_e32 v86, v86, v96
	v_mul_f32_e32 v87, v87, v96
	v_mul_f32_e32 v68, v68, v84
	v_mul_f32_e32 v69, v69, v85
	v_mul_f32_e32 v74, v74, v70
	v_mul_f32_e32 v75, v75, v71
	v_cvt_pk_bf16_f32 v72, v72, v73
	v_cvt_pk_bf16_f32 v73, v74, v75
	v_mul_f32_e32 v70, v70, v86
	v_mul_f32_e32 v71, v71, v87
	global_store_dwordx2 v[58:59], v[72:73], off
	v_cvt_pk_bf16_f32 v68, v68, v69
	v_cvt_pk_bf16_f32 v69, v70, v71
	global_store_dwordx2 v[60:61], v[68:69], off
	global_load_dwordx4 v[68:71], v[48:49], off offset:1024
	v_mul_f32_e32 v72, v76, v43
	v_mul_f32_e32 v73, v77, v43
	v_mul_f32_e32 v74, v78, v43
	v_mul_f32_e32 v75, v79, v43
	v_mul_f32_e32 v76, v88, v96
	v_mul_f32_e32 v77, v89, v96
	v_mul_f32_e32 v78, v90, v96
	v_mul_f32_e32 v79, v91, v96
	v_mul_f32_e32 v36, v36, v43
	v_mul_f32_e32 v37, v37, v43
	v_mul_f32_e32 v38, v38, v43
	v_mul_f32_e32 v39, v39, v43
	v_mul_f32_e32 v32, v32, v96
	v_mul_f32_e32 v33, v33, v96
	v_mul_f32_e32 v34, v34, v96
	v_mul_f32_e32 v35, v35, v96
	v_mul_f32_e32 v28, v28, v43
	v_mul_f32_e32 v29, v29, v43
	v_mul_f32_e32 v30, v30, v43
	v_mul_f32_e32 v31, v31, v43
	v_mul_f32_e32 v24, v24, v96
	v_mul_f32_e32 v25, v25, v96
	v_mul_f32_e32 v26, v26, v96
	v_mul_f32_e32 v27, v27, v96
	v_mul_f32_e32 v20, v20, v43
	v_mul_f32_e32 v21, v21, v43
	v_mul_f32_e32 v22, v22, v43
	v_mul_f32_e32 v23, v23, v43
	v_mul_f32_e32 v16, v16, v96
	v_mul_f32_e32 v17, v17, v96
	v_mul_f32_e32 v18, v18, v96
	v_mul_f32_e32 v19, v19, v96
	v_mul_f32_e32 v12, v12, v43
	v_mul_f32_e32 v13, v13, v43
	v_mul_f32_e32 v14, v14, v43
	v_mul_f32_e32 v15, v15, v43
	v_mul_f32_e32 v8, v8, v96
	v_mul_f32_e32 v9, v9, v96
	v_mul_f32_e32 v10, v10, v96
	v_mul_f32_e32 v11, v11, v96
	v_mul_f32_e32 v0, v0, v43
	v_mul_f32_e32 v1, v1, v43
	v_mul_f32_e32 v2, v2, v43
	v_mul_f32_e32 v3, v3, v43
	v_mul_f32_e32 v4, v4, v96
	v_mul_f32_e32 v5, v5, v96
	v_mul_f32_e32 v6, v6, v96
	v_mul_f32_e32 v7, v7, v96
	s_waitcnt vmcnt(0)
	v_mul_f32_e32 v72, v72, v68
	v_mul_f32_e32 v73, v73, v69
	v_mul_f32_e32 v74, v74, v70
	v_mul_f32_e32 v75, v75, v71
	v_mul_f32_e32 v76, v76, v68
	v_mul_f32_e32 v77, v77, v69
	v_cvt_pk_bf16_f32 v68, v72, v73
	v_cvt_pk_bf16_f32 v69, v74, v75
	v_mul_f32_e32 v70, v78, v70
	v_mul_f32_e32 v71, v79, v71
	global_store_dwordx2 v[58:59], v[68:69], off offset:512
	v_cvt_pk_bf16_f32 v68, v76, v77
	v_cvt_pk_bf16_f32 v69, v70, v71
	global_store_dwordx2 v[60:61], v[68:69], off offset:512
	global_load_dwordx4 v[68:71], v[48:49], off offset:2048
	v_mul_f32_e32 v72, v80, v43
	v_mul_f32_e32 v73, v81, v43
	v_mul_f32_e32 v74, v82, v43
	v_mul_f32_e32 v75, v83, v43
	v_mul_f32_e32 v76, v92, v96
	v_mul_f32_e32 v77, v93, v96
	v_mul_f32_e32 v78, v94, v96
	v_mul_f32_e32 v79, v95, v96
	s_waitcnt vmcnt(0)
	v_mul_f32_e32 v72, v72, v68
	v_mul_f32_e32 v73, v73, v69
	v_mul_f32_e32 v74, v74, v70
	v_mul_f32_e32 v75, v75, v71
	v_mul_f32_e32 v76, v76, v68
	v_mul_f32_e32 v77, v77, v69
	v_cvt_pk_bf16_f32 v68, v72, v73
	v_cvt_pk_bf16_f32 v69, v74, v75
	v_mul_f32_e32 v70, v78, v70
	v_mul_f32_e32 v71, v79, v71
	global_store_dwordx2 v[58:59], v[68:69], off offset:1024
	v_cvt_pk_bf16_f32 v68, v76, v77
	v_cvt_pk_bf16_f32 v69, v70, v71
	global_store_dwordx2 v[60:61], v[68:69], off offset:1024
	global_load_dwordx4 v[68:71], v[48:49], off offset:3072
	s_waitcnt vmcnt(0)
	v_mul_f32_e32 v36, v36, v68
	v_mul_f32_e32 v37, v37, v69
	v_mul_f32_e32 v38, v38, v70
	v_mul_f32_e32 v39, v39, v71
	v_mul_f32_e32 v68, v32, v68
	v_mul_f32_e32 v69, v33, v69
	v_cvt_pk_bf16_f32 v32, v36, v37
	v_cvt_pk_bf16_f32 v33, v38, v39
	v_mul_f32_e32 v34, v34, v70
	v_mul_f32_e32 v35, v35, v71
	global_store_dwordx2 v[58:59], v[32:33], off offset:1536
	v_cvt_pk_bf16_f32 v32, v68, v69
	v_cvt_pk_bf16_f32 v33, v34, v35
	global_store_dwordx2 v[60:61], v[32:33], off offset:1536
	global_load_dwordx4 v[32:35], v[50:51], off
	s_waitcnt vmcnt(0)
	v_mul_f32_e32 v28, v28, v32
	v_mul_f32_e32 v29, v29, v33
	v_mul_f32_e32 v30, v30, v34
	v_mul_f32_e32 v31, v31, v35
	v_mul_f32_e32 v32, v24, v32
	v_mul_f32_e32 v33, v25, v33
	v_cvt_pk_bf16_f32 v24, v28, v29
	v_cvt_pk_bf16_f32 v25, v30, v31
	v_mul_f32_e32 v26, v26, v34
	v_mul_f32_e32 v27, v27, v35
	global_store_dwordx2 v[58:59], v[24:25], off offset:2048
	v_cvt_pk_bf16_f32 v24, v32, v33
	v_cvt_pk_bf16_f32 v25, v26, v27
	global_store_dwordx2 v[60:61], v[24:25], off offset:2048
	global_load_dwordx4 v[24:27], v[52:53], off
	s_waitcnt vmcnt(0)
	v_mul_f32_e32 v20, v20, v24
	v_mul_f32_e32 v21, v21, v25
	v_mul_f32_e32 v22, v22, v26
	v_mul_f32_e32 v23, v23, v27
	v_mul_f32_e32 v24, v16, v24
	v_mul_f32_e32 v25, v17, v25
	v_cvt_pk_bf16_f32 v16, v20, v21
	v_cvt_pk_bf16_f32 v17, v22, v23
	v_mul_f32_e32 v18, v18, v26
	v_mul_f32_e32 v19, v19, v27
	global_store_dwordx2 v[58:59], v[16:17], off offset:2560
	v_cvt_pk_bf16_f32 v16, v24, v25
	v_cvt_pk_bf16_f32 v17, v18, v19
	global_store_dwordx2 v[60:61], v[16:17], off offset:2560
	global_load_dwordx4 v[16:19], v[54:55], off
	s_waitcnt vmcnt(0)
	v_mul_f32_e32 v12, v12, v16
	v_mul_f32_e32 v13, v13, v17
	v_mul_f32_e32 v14, v14, v18
	v_mul_f32_e32 v15, v15, v19
	v_mul_f32_e32 v16, v8, v16
	v_mul_f32_e32 v17, v9, v17
	v_cvt_pk_bf16_f32 v8, v12, v13
	v_cvt_pk_bf16_f32 v9, v14, v15
	v_mul_f32_e32 v10, v10, v18
	v_mul_f32_e32 v11, v11, v19
	global_store_dwordx2 v[58:59], v[8:9], off offset:3072
	v_cvt_pk_bf16_f32 v8, v16, v17
	v_cvt_pk_bf16_f32 v9, v10, v11
	global_store_dwordx2 v[60:61], v[8:9], off offset:3072
	global_load_dwordx4 v[8:11], v[56:57], off
	s_waitcnt vmcnt(0)
	v_mul_f32_e32 v0, v0, v8
	v_mul_f32_e32 v1, v1, v9
	v_mul_f32_e32 v2, v2, v10
	v_mul_f32_e32 v3, v3, v11
	v_cvt_pk_bf16_f32 v0, v0, v1
	v_cvt_pk_bf16_f32 v1, v2, v3
	v_mul_f32_e32 v4, v4, v8
	v_mul_f32_e32 v5, v5, v9
	v_mul_f32_e32 v6, v6, v10
	v_mul_f32_e32 v7, v7, v11
	global_store_dwordx2 v[58:59], v[0:1], off offset:3584
	v_cvt_pk_bf16_f32 v0, v4, v5
	v_cvt_pk_bf16_f32 v1, v6, v7
	global_store_dwordx2 v[60:61], v[0:1], off offset:3584
	s_cbranch_scc0 .LBB0_75
